# seams: non-last workgroups poll the top-level generation word directly instead of the per-XCD word
# speedup vs baseline: 1.0095x; 1.0043x over previous
.LBB0_73:
	s_or_b64 exec, exec, s[10:11]
	v_cvt_f32_u32_e32 v6, v4
	s_waitcnt vmcnt(0)
	v_readfirstlane_b32 s8, v5
	v_sub_u32_e32 v5, 0, v4
	v_rcp_iflag_f32_e32 v6, v6
	v_add_u32_e32 v7, s8, v3
	v_mul_f32_e32 v6, 0x4f7ffffe, v6
	v_cvt_u32_f32_e32 v6, v6
	v_mul_lo_u32 v3, v5, v6
	v_mul_hi_u32 v3, v6, v3
	v_add_u32_e32 v3, v6, v3
	v_mul_hi_u32 v3, v7, v3
	v_mul_lo_u32 v5, v3, v4
	v_sub_u32_e32 v5, v7, v5
	v_add_u32_e32 v6, 1, v3
	v_cmp_ge_u32_e32 vcc, v5, v4
	s_nop 1
	v_cndmask_b32_e32 v3, v3, v6, vcc
	v_sub_u32_e32 v6, v5, v4
	v_cndmask_b32_e32 v5, v5, v6, vcc
	v_add_u32_e32 v6, 1, v3
	v_cmp_ge_u32_e32 vcc, v5, v4
	v_add_u32_e32 v5, 1, v7
	s_nop 0
	v_cndmask_b32_e32 v3, v3, v6, vcc
	v_mul_lo_u32 v6, v4, v3
	v_add_u32_e32 v4, v6, v4
	v_cmp_ne_u32_e32 vcc, v5, v4
	s_and_saveexec_b64 s[8:9], vcc
	s_xor_b64 s[8:9], exec, s[8:9]
	s_cbranch_execz .LBB0_87
	s_waitcnt lgkmcnt(0)
	s_add_u32 s14, s40, 0x1e03500
	s_addc_u32 s15, s41, 0
	v_mov_b32_e32 v2, 0
	global_load_dword v2, v2, s[14:15] sc1
	s_waitcnt vmcnt(0)
	v_cmp_eq_u32_e32 vcc, v2, v3
	s_and_saveexec_b64 s[10:11], vcc
	s_cbranch_execz .LBB0_86
	s_add_u32 s12, s40, 0x1e00200
	s_addc_u32 s13, s41, 0
	s_mov_b32 s26, 1
	s_mov_b64 s[16:17], 0
	v_mov_b32_e32 v2, 0
	s_branch .LBB0_77

.LBB0_864:
	s_or_b64 exec, exec, s[8:9]
	v_cvt_f32_u32_e32 v6, v4
	s_waitcnt vmcnt(0)
	v_readfirstlane_b32 s6, v5
	v_sub_u32_e32 v5, 0, v4
	v_rcp_iflag_f32_e32 v6, v6
	v_add_u32_e32 v7, s6, v3
	v_mul_f32_e32 v6, 0x4f7ffffe, v6
	v_cvt_u32_f32_e32 v6, v6
	v_mul_lo_u32 v3, v5, v6
	v_mul_hi_u32 v3, v6, v3
	v_add_u32_e32 v3, v6, v3
	v_mul_hi_u32 v3, v7, v3
	v_mul_lo_u32 v5, v3, v4
	v_sub_u32_e32 v5, v7, v5
	v_add_u32_e32 v6, 1, v3
	v_cmp_ge_u32_e32 vcc, v5, v4
	s_nop 1
	v_cndmask_b32_e32 v3, v3, v6, vcc
	v_sub_u32_e32 v6, v5, v4
	v_cndmask_b32_e32 v5, v5, v6, vcc
	v_add_u32_e32 v6, 1, v3
	v_cmp_ge_u32_e32 vcc, v5, v4
	v_add_u32_e32 v5, 1, v7
	s_nop 0
	v_cndmask_b32_e32 v3, v3, v6, vcc
	v_mul_lo_u32 v6, v4, v3
	v_add_u32_e32 v4, v6, v4
	v_cmp_ne_u32_e32 vcc, v5, v4
	s_and_saveexec_b64 s[6:7], vcc
	s_xor_b64 s[6:7], exec, s[6:7]
	s_cbranch_execz .LBB0_878
	s_waitcnt lgkmcnt(0)
	s_add_u32 s12, s40, 0x1e03500
	s_addc_u32 s13, s41, 0
	v_mov_b32_e32 v2, 0
	global_load_dword v2, v2, s[12:13] sc1
	s_waitcnt vmcnt(0)
	v_cmp_eq_u32_e32 vcc, v2, v3
	s_and_saveexec_b64 s[8:9], vcc
	s_cbranch_execz .LBB0_877
	s_add_u32 s10, s40, 0x1e00200
	s_addc_u32 s11, s41, 0
	s_mov_b32 s24, 1
	s_mov_b64 s[14:15], 0
	v_mov_b32_e32 v2, 0
	s_branch .LBB0_868

.LBB0_1082:
	s_or_b64 exec, exec, s[6:7]
	v_cvt_f32_u32_e32 v4, v2
	s_waitcnt vmcnt(0)
	v_readfirstlane_b32 s6, v3
	v_sub_u32_e32 v3, 0, v2
	v_rcp_iflag_f32_e32 v4, v4
	v_add_u32_e32 v5, s6, v1
	v_mul_f32_e32 v4, 0x4f7ffffe, v4
	v_cvt_u32_f32_e32 v4, v4
	v_mul_lo_u32 v1, v3, v4
	v_mul_hi_u32 v1, v4, v1
	v_add_u32_e32 v1, v4, v1
	v_mul_hi_u32 v1, v5, v1
	v_mul_lo_u32 v3, v1, v2
	v_sub_u32_e32 v3, v5, v3
	v_add_u32_e32 v4, 1, v1
	v_cmp_ge_u32_e32 vcc, v3, v2
	s_nop 1
	v_cndmask_b32_e32 v1, v1, v4, vcc
	v_sub_u32_e32 v4, v3, v2
	v_cndmask_b32_e32 v3, v3, v4, vcc
	v_add_u32_e32 v4, 1, v1
	v_cmp_ge_u32_e32 vcc, v3, v2
	v_add_u32_e32 v3, 1, v5
	s_nop 0
	v_cndmask_b32_e32 v1, v1, v4, vcc
	v_mul_lo_u32 v4, v2, v1
	v_add_u32_e32 v2, v4, v2
	v_cmp_ne_u32_e32 vcc, v3, v2
	s_and_saveexec_b64 s[6:7], vcc
	s_xor_b64 s[6:7], exec, s[6:7]
	s_cbranch_execz .LBB0_1096
	s_waitcnt lgkmcnt(0)
	v_readlane_b32 s98, v253, 45
	v_readlane_b32 s99, v253, 46
	s_nop 4
	global_load_dword v0, v139, s[98:99] sc1
	s_waitcnt vmcnt(0)
	v_cmp_eq_u32_e32 vcc, v0, v1
	s_and_saveexec_b64 s[8:9], vcc
	s_cbranch_execz .LBB0_1095
	s_mov_b32 s23, 1
	s_mov_b64 s[10:11], 0
	s_branch .LBB0_1086

.LBB0_1088:
	global_load_dword v0, v139, s[98:99] sc1
	s_add_i32 s23, s23, 1
	s_mov_b64 s[18:19], -1
	s_waitcnt vmcnt(0)
	v_cmp_ne_u32_e32 vcc, v0, v1
	s_orn2_b64 s[14:15], vcc, exec
	s_branch .LBB0_1085

.LBB0_1461:
	s_or_b64 exec, exec, s[4:5]
	v_cvt_f32_u32_e32 v4, v2
	s_waitcnt vmcnt(0)
	v_readfirstlane_b32 s4, v3
	v_sub_u32_e32 v3, 0, v2
	v_rcp_iflag_f32_e32 v4, v4
	v_add_u32_e32 v5, s4, v1
	v_mul_f32_e32 v4, 0x4f7ffffe, v4
	v_cvt_u32_f32_e32 v4, v4
	v_mul_lo_u32 v1, v3, v4
	v_mul_hi_u32 v1, v4, v1
	v_add_u32_e32 v1, v4, v1
	v_mul_hi_u32 v1, v5, v1
	v_mul_lo_u32 v3, v1, v2
	v_sub_u32_e32 v3, v5, v3
	v_add_u32_e32 v4, 1, v1
	v_cmp_ge_u32_e32 vcc, v3, v2
	s_nop 1
	v_cndmask_b32_e32 v1, v1, v4, vcc
	v_sub_u32_e32 v4, v3, v2
	v_cndmask_b32_e32 v3, v3, v4, vcc
	v_add_u32_e32 v4, 1, v1
	v_cmp_ge_u32_e32 vcc, v3, v2
	v_add_u32_e32 v3, 1, v5
	s_nop 0
	v_cndmask_b32_e32 v1, v1, v4, vcc
	v_mul_lo_u32 v4, v2, v1
	v_add_u32_e32 v2, v4, v2
	v_cmp_ne_u32_e32 vcc, v3, v2
	s_and_saveexec_b64 s[4:5], vcc
	s_xor_b64 s[4:5], exec, s[4:5]
	s_cbranch_execz .LBB0_1475
	s_waitcnt lgkmcnt(0)
	v_readlane_b32 s98, v253, 45
	v_readlane_b32 s99, v253, 46
	s_nop 4
	global_load_dword v0, v139, s[98:99] sc1
	s_waitcnt vmcnt(0)
	v_cmp_eq_u32_e32 vcc, v0, v1
	s_and_saveexec_b64 s[6:7], vcc
	s_cbranch_execz .LBB0_1474
	s_mov_b32 s20, 1
	s_mov_b64 s[8:9], 0
	s_branch .LBB0_1465

.LBB0_1467:
	global_load_dword v0, v139, s[98:99] sc1
	s_add_i32 s20, s20, 1
	s_mov_b64 s[14:15], -1
	s_waitcnt vmcnt(0)
	v_cmp_ne_u32_e32 vcc, v0, v1
	s_orn2_b64 s[12:13], vcc, exec
	s_branch .LBB0_1464
